# chunk-prep stage A: fragment and decay-table LDS reads issued up front with counted waits (waves 0-5), KtT loop one wait per iteration (waves 6-7); on v46 stack
# baseline (speedup 1.0000x reference)
; #define GAS __attribute__((address_space(1)))
; #define LAS __attribute__((address_space(3)))
; __device__ __forceinline__ unsigned f2bf(float f) { unsigned u = __builtin_bit_cast(unsigned, f); return (u + 0x7fffu + ((u >> 16) & 1u)) >> 16; }
; __device__ __forceinline__ unsigned gcvtpk(float lo, float hi) { gf32x2 v = {lo, hi}; gbf16x2 b = __builtin_convertvector(v, gbf16x2); return __builtin_bit_cast(unsigned, b); }
; __device__ __forceinline__ int gcrow(int r, int hi) { return (r & 3) + 8 * (r >> 2) + 4 * hi; }
; __device__ __forceinline__ void gdn_chunk_prep(Frame& F) {
;     ...
;         if (wave < 6) {
;             const int typ = wave / 3, blk = wave % 3, I = blk ? 1 : 0, J = blk == 2 ? 1 : 0;
;             const LAS unsigned char* Ap = (typ ? qs : ks) + (32 * I + r32) * TS + hi * 16;
;             const LAS unsigned char* Bp = ks + (32 * J + r32) * TS + hi * 16;
;             gf32x16 acc = {};
; #pragma unroll
;             for (int kk = 0; kk < 8; ++kk) {
;                 const gbf16x8 a = *(const LAS gbf16x8*)(Ap + kk * 32), bq = *(const LAS gbf16x8*)(Bp + kk * 32);
;                 acc = __builtin_amdgcn_mfma_f32_32x32x16_bf16(a, bq, acc, 0, 0, 0);
;             }
;             const int j = 32 * J + r32; const float Gj = Gs[j];
; #pragma unroll
;             for (int q = 0; q < 16; ++q) {
;                 const int i = 32 * I + gcrow(q, hi);
;                 const float val = acc[q] * __expf(Gs[i] - Gj);
;                 if (typ == 0) { if (i > j) Amat[i * 68 + j] = Bs[i] * val; }
;                 else { *(LAS bf16*)((LAS unsigned char*)Tb + i * RS_K + j * 2) = (bf16)f2bf(i >= j ? val : 0.f); }
;             }
;     ...
;             const int t = tid_ - 384;
; #pragma unroll 4
;             for (int ig = 0; ig < 16; ++ig) {
;                 const float x0 = gbf(*(const LAS bf16*)(ks + (4 * ig) * TS + t * 2)) * EGTs[4 * ig], x1 = gbf(*(const LAS bf16*)(ks + (4 * ig + 1) * TS + t * 2)) * EGTs[4 * ig + 1];
;                 const float x2 = gbf(*(const LAS bf16*)(ks + (4 * ig + 2) * TS + t * 2)) * EGTs[4 * ig + 2], x3 = gbf(*(const LAS bf16*)(ks + (4 * ig + 3) * TS + t * 2)) * EGTs[4 * ig + 3];
;                 v2u w = {gcvtpk(x0, x1), gcvtpk(x2, x3)};
;                 *(GAS v2u*)(CH + CH_KT + t * RS_K + ig * 8) = w;
;             }
.LBB0_945:
	v_add_u32_e32 v18, s2, v4
	ds_read_b128 v[6:9], v18
	ds_read_b128 v[10:13], v18 offset:16
	ds_read_b128 v[14:17], v18 offset:32
	ds_read_b128 v[18:21], v18 offset:48
	ds_read_u16 v24, v5
	ds_read_u16 v25, v5 offset:272
	ds_read_u16 v26, v5 offset:544
	ds_read_u16 v27, v5 offset:816
	ds_read_u16 v28, v5 offset:1088
	ds_read_u16 v29, v5 offset:1360
	ds_read_u16 v30, v5 offset:1632
	ds_read_u16 v31, v5 offset:1904
	ds_read_u16 v32, v5 offset:2176
	ds_read_u16 v33, v5 offset:2448
	ds_read_u16 v34, v5 offset:2720
	ds_read_u16 v35, v5 offset:2992
	ds_read_u16 v36, v5 offset:3264
	ds_read_u16 v37, v5 offset:3536
	ds_read_u16 v38, v5 offset:3808
	ds_read_u16 v39, v5 offset:4080
	s_waitcnt lgkmcnt(0)
	v_lshlrev_b32_e32 v24, 16, v24
	v_lshlrev_b32_e32 v25, 16, v25
	v_lshlrev_b32_e32 v26, 16, v26
	v_lshlrev_b32_e32 v27, 16, v27
	v_lshlrev_b32_e32 v28, 16, v28
	v_lshlrev_b32_e32 v29, 16, v29
	v_lshlrev_b32_e32 v30, 16, v30
	v_lshlrev_b32_e32 v31, 16, v31
	v_lshlrev_b32_e32 v32, 16, v32
	v_lshlrev_b32_e32 v33, 16, v33
	v_lshlrev_b32_e32 v34, 16, v34
	v_lshlrev_b32_e32 v35, 16, v35
	v_lshlrev_b32_e32 v36, 16, v36
	v_lshlrev_b32_e32 v37, 16, v37
	v_lshlrev_b32_e32 v38, 16, v38
	v_lshlrev_b32_e32 v39, 16, v39
	v_pk_mul_f32 v[6:7], v[6:7], v[24:25]
	v_pk_mul_f32 v[8:9], v[8:9], v[26:27]
	v_pk_mul_f32 v[10:11], v[10:11], v[28:29]
	v_pk_mul_f32 v[12:13], v[12:13], v[30:31]
	v_pk_mul_f32 v[14:15], v[14:15], v[32:33]
	v_pk_mul_f32 v[16:17], v[16:17], v[34:35]
	v_pk_mul_f32 v[18:19], v[18:19], v[36:37]
	v_pk_mul_f32 v[20:21], v[20:21], v[38:39]
	v_cvt_pk_bf16_f32 v6, v6, v7
	v_cvt_pk_bf16_f32 v7, v8, v9
	v_cvt_pk_bf16_f32 v8, v10, v11
	v_cvt_pk_bf16_f32 v9, v12, v13
	v_cvt_pk_bf16_f32 v10, v14, v15
	v_cvt_pk_bf16_f32 v11, v16, v17
	v_cvt_pk_bf16_f32 v12, v18, v19
	v_cvt_pk_bf16_f32 v13, v20, v21
	global_store_dwordx4 v[2:3], v[6:9], off offset:-16
	global_store_dwordx4 v[2:3], v[10:13], off
	v_add_u32_e32 v5, 0x1100, v5
	v_lshl_add_u64 v[2:3], v[2:3], 0, 32
	s_add_i32 s2, s2, 64
	s_cmpk_lg_i32 s2, 0x100
	s_cbranch_scc1 .LBB0_945
	s_mov_b64 s[6:7], 0
.LBB0_947:
	s_and_b32 s2, s94, 1
	s_lshl_b32 s11, s2, 10
	s_add_i32 s89, s11, 0
	s_mul_i32 s10, s2, 0xc800
	v_bfe_u32 v124, v129, 5, 1
	s_add_i32 s95, s89, s10
	v_and_b32_e32 v126, 31, v129
	s_add_i32 s88, s95, 0xb400
	v_lshlrev_b32_e32 v125, 4, v124
	s_and_b64 vcc, exec, s[6:7]
	s_cbranch_vccz .LBB0_1044
	v_readlane_b32 s0, v252, 58
	s_add_i32 s10, s95, 0x7000
	v_lshl_or_b32 v21, v124, 2, s90
	v_or_b32_e32 v19, s0, v126
	v_lshlrev_b32_e32 v2, 2, v19
	v_readlane_b32 s0, v252, 54
	v_add_u32_e32 v18, 0, v2
	v_add_u32_e32 v30, s89, v2
	v_mul_u32_u24_e32 v2, 0x110, v19
	v_readlane_b32 s1, v252, 55
	v_add3_u32 v31, s95, v2, v125
	s_and_b64 s[6:7], s[0:1], exec
	v_or_b32_e32 v2, s90, v126
	s_cselect_b32 s6, s88, s10
	v_mul_u32_u24_e32 v2, 0x110, v2
	v_lshlrev_b32_e32 v3, 1, v19
	v_add3_u32 v32, s6, v2, v125
	v_sub_u32_e32 v20, v18, v3
	v_lshl_add_u32 v33, v21, 2, s89
	ds_read_b128 v[34:37], v33
	ds_read_b128 v[38:41], v33 offset:32
	ds_read_b128 v[42:45], v33 offset:64
	ds_read_b128 v[46:49], v33 offset:96
	ds_read_b128 v[50:53], v33 offset:256
	ds_read_b128 v[54:57], v33 offset:288
	ds_read_b128 v[58:61], v33 offset:320
	ds_read_b128 v[62:65], v33 offset:352
	ds_read_b128 v[2:5], v32
	ds_read_b128 v[6:9], v31 offset:46080
	ds_read_b128 v[22:25], v32 offset:32
	ds_read_b128 v[26:29], v31 offset:46112
	ds_read_b128 v[66:69], v32 offset:64
	ds_read_b128 v[70:73], v31 offset:46144
	ds_read_b128 v[74:77], v32 offset:96
	ds_read_b128 v[78:81], v31 offset:46176
	ds_read_b128 v[82:85], v32 offset:128
	ds_read_b128 v[86:89], v31 offset:46208
	ds_read_b128 v[90:93], v32 offset:160
	ds_read_b128 v[94:97], v31 offset:46240
	ds_read_b128 v[98:101], v32 offset:192
	ds_read_b128 v[102:105], v31 offset:46272
	ds_read_b128 v[106:109], v32 offset:224
	ds_read_b128 v[110:113], v31 offset:46304
	s_waitcnt lgkmcnt(14)
	v_mfma_f32_32x32x16_bf16 v[2:17], v[2:5], v[6:9], 0
	v_readlane_b32 s0, v252, 56
	v_readlane_b32 s1, v252, 57
	s_mov_b64 s[6:7], -1
	s_and_b64 vcc, exec, s[0:1]
	v_cmp_ge_u32_e64 s[28:29], v21, v19
	s_waitcnt lgkmcnt(12)
	v_mfma_f32_32x32x16_bf16 v[2:17], v[22:25], v[26:29], v[2:17]
	s_waitcnt lgkmcnt(10)
	v_mfma_f32_32x32x16_bf16 v[2:17], v[66:69], v[70:73], v[2:17]
	s_waitcnt lgkmcnt(8)
	v_mfma_f32_32x32x16_bf16 v[2:17], v[74:77], v[78:81], v[2:17]
	s_waitcnt lgkmcnt(6)
	v_mfma_f32_32x32x16_bf16 v[2:17], v[82:85], v[86:89], v[2:17]
	s_waitcnt lgkmcnt(4)
	v_mfma_f32_32x32x16_bf16 v[2:17], v[90:93], v[94:97], v[2:17]
	s_waitcnt lgkmcnt(2)
	v_mfma_f32_32x32x16_bf16 v[2:17], v[98:101], v[102:105], v[2:17]
	s_waitcnt lgkmcnt(0)
	v_mfma_f32_32x32x16_bf16 v[2:17], v[106:109], v[110:113], v[2:17]
	v_lshl_add_u32 v23, v21, 2, s89
	ds_read_b32 v22, v30
	v_mov_b32_e32 v24, v34
	s_waitcnt lgkmcnt(0)
	v_sub_f32_e32 v24, v24, v22
	v_mul_f32_e32 v24, 0x3fb8aa3b, v24
	v_exp_f32_e32 v24, v24
	s_nop 4
	v_mul_f32_e32 v2, v2, v24
	s_cbranch_vccz .LBB0_950
	v_cndmask_b32_e64 v24, 0, v2, s[28:29]
	v_bfe_u32 v25, v24, 16, 1
	v_add3_u32 v24, v24, v25, s84
	v_mad_u32_u24 v25, v21, s96, v20
	ds_write_b16_d16_hi v25, v24 offset:19456
	s_mov_b64 s[6:7], 0
.LBB0_950:
	s_andn2_b64 vcc, exec, s[6:7]
	s_cbranch_vccnz .LBB0_954
	v_cmp_gt_u32_e32 vcc, v21, v19
	s_and_saveexec_b64 s[6:7], vcc
	s_cbranch_execz .LBB0_953
	v_mov_b32_e32 v24, v50
	v_mad_u32_u24 v25, v21, s27, v18
	v_mul_f32_e32 v2, v2, v24
	ds_write_b32 v25, v2 offset:2048

; #define LAS __attribute__((address_space(3)))
; __device__ __forceinline__ unsigned f2bf(float f) { unsigned u = __builtin_bit_cast(unsigned, f); return (u + 0x7fffu + ((u >> 16) & 1u)) >> 16; }
; __device__ __forceinline__ int gcrow(int r, int hi) { return (r & 3) + 8 * (r >> 2) + 4 * hi; }
; __device__ __forceinline__ void gdn_chunk_prep(Frame& F) {
;     ...
;             const int j = 32 * J + r32; const float Gj = Gs[j];
; #pragma unroll
;             for (int q = 0; q < 16; ++q) {
;                 const int i = 32 * I + gcrow(q, hi);
;                 const float val = acc[q] * __expf(Gs[i] - Gj);
;                 if (typ == 0) { if (i > j) Amat[i * 68 + j] = Bs[i] * val; }
;                 else { *(LAS bf16*)((LAS unsigned char*)Tb + i * RS_K + j * 2) = (bf16)f2bf(i >= j ? val : 0.f); }
;             }
.LBB0_954:
	v_mov_b32_e32 v24, v35
	v_readlane_b32 s0, v252, 56
	v_readlane_b32 s1, v252, 57
	v_or_b32_e32 v2, 1, v21
	s_andn2_b64 vcc, exec, s[0:1]
	v_sub_f32_e32 v24, v24, v22
	v_mul_f32_e32 v24, 0x3fb8aa3b, v24
	v_exp_f32_e32 v24, v24
	v_cndmask_b32_e64 v25, 0, 1, s[0:1]
	v_cmp_ne_u32_e64 s[28:29], 1, v25
	s_mov_b64 s[6:7], -1
	v_mul_f32_e32 v3, v3, v24
	s_cbranch_vccnz .LBB0_956
	v_cmp_ge_u32_e32 vcc, v2, v19
	s_mov_b64 s[6:7], 0
	s_nop 0
	v_cndmask_b32_e32 v24, 0, v3, vcc
	v_bfe_u32 v25, v24, 16, 1
	v_add3_u32 v24, v24, v25, s84
	v_mad_u32_u24 v25, v2, s96, v20
	ds_write_b16_d16_hi v25, v24 offset:19456
.LBB0_956:
	s_andn2_b64 vcc, exec, s[6:7]
	s_cbranch_vccnz .LBB0_960
	v_cmp_ge_u32_e32 vcc, v21, v19
	s_and_saveexec_b64 s[6:7], vcc
	s_cbranch_execz .LBB0_959
	v_mov_b32_e32 v24, v51
	v_mad_u32_u24 v2, v2, s27, v18
	v_mul_f32_e32 v3, v3, v24
	ds_write_b32 v2, v3 offset:2048

; #define LAS __attribute__((address_space(3)))
; __device__ __forceinline__ unsigned f2bf(float f) { unsigned u = __builtin_bit_cast(unsigned, f); return (u + 0x7fffu + ((u >> 16) & 1u)) >> 16; }
; __device__ __forceinline__ int gcrow(int r, int hi) { return (r & 3) + 8 * (r >> 2) + 4 * hi; }
; __device__ __forceinline__ void gdn_chunk_prep(Frame& F) {
;     ...
;             const int j = 32 * J + r32; const float Gj = Gs[j];
; #pragma unroll
;             for (int q = 0; q < 16; ++q) {
;                 const int i = 32 * I + gcrow(q, hi);
;                 const float val = acc[q] * __expf(Gs[i] - Gj);
;                 if (typ == 0) { if (i > j) Amat[i * 68 + j] = Bs[i] * val; }
;                 else { *(LAS bf16*)((LAS unsigned char*)Tb + i * RS_K + j * 2) = (bf16)f2bf(i >= j ? val : 0.f); }
;             }
.LBB0_960:
	v_mov_b32_e32 v2, v36
	s_and_b64 vcc, exec, s[28:29]
	s_mov_b64 s[6:7], -1
	v_sub_f32_e32 v2, v2, v22
	v_mul_f32_e32 v2, 0x3fb8aa3b, v2
	v_exp_f32_e32 v3, v2
	v_or_b32_e32 v2, 2, v21
	v_mul_f32_e32 v3, v4, v3
	s_cbranch_vccnz .LBB0_962
	v_cmp_ge_u32_e32 vcc, v2, v19
	s_mov_b64 s[6:7], 0
	s_nop 0
	v_cndmask_b32_e32 v4, 0, v3, vcc
	v_bfe_u32 v24, v4, 16, 1
	v_add3_u32 v4, v4, v24, s84
	v_mad_u32_u24 v24, v2, s96, v20
	ds_write_b16_d16_hi v24, v4 offset:19456
.LBB0_962:
	s_andn2_b64 vcc, exec, s[6:7]
	s_cbranch_vccnz .LBB0_966
	v_cmp_gt_u32_e32 vcc, v2, v19
	s_and_saveexec_b64 s[6:7], vcc
	s_cbranch_execz .LBB0_965
	v_mov_b32_e32 v4, v52
	v_mad_u32_u24 v2, v2, s27, v18
	v_mul_f32_e32 v3, v3, v4
	ds_write_b32 v2, v3 offset:2048

; #define LAS __attribute__((address_space(3)))
; __device__ __forceinline__ unsigned f2bf(float f) { unsigned u = __builtin_bit_cast(unsigned, f); return (u + 0x7fffu + ((u >> 16) & 1u)) >> 16; }
; __device__ __forceinline__ int gcrow(int r, int hi) { return (r & 3) + 8 * (r >> 2) + 4 * hi; }
; __device__ __forceinline__ void gdn_chunk_prep(Frame& F) {
;     ...
;             const int j = 32 * J + r32; const float Gj = Gs[j];
; #pragma unroll
;             for (int q = 0; q < 16; ++q) {
;                 const int i = 32 * I + gcrow(q, hi);
;                 const float val = acc[q] * __expf(Gs[i] - Gj);
;                 if (typ == 0) { if (i > j) Amat[i * 68 + j] = Bs[i] * val; }
;                 else { *(LAS bf16*)((LAS unsigned char*)Tb + i * RS_K + j * 2) = (bf16)f2bf(i >= j ? val : 0.f); }
;             }
.LBB0_966:
	v_mov_b32_e32 v2, v37
	s_and_b64 vcc, exec, s[28:29]
	s_mov_b64 s[6:7], -1
	v_sub_f32_e32 v2, v2, v22
	v_mul_f32_e32 v2, 0x3fb8aa3b, v2
	v_exp_f32_e32 v3, v2
	v_or_b32_e32 v2, 3, v21
	v_mul_f32_e32 v3, v5, v3
	s_cbranch_vccnz .LBB0_968
	v_cmp_ge_u32_e32 vcc, v2, v19
	s_mov_b64 s[6:7], 0
	s_nop 0
	v_cndmask_b32_e32 v4, 0, v3, vcc
	v_bfe_u32 v5, v4, 16, 1
	v_add3_u32 v4, v4, v5, s84
	v_mad_u32_u24 v5, v2, s96, v20
	ds_write_b16_d16_hi v5, v4 offset:19456
.LBB0_968:
	s_andn2_b64 vcc, exec, s[6:7]
	s_cbranch_vccnz .LBB0_972
	v_cmp_gt_u32_e32 vcc, v2, v19
	s_and_saveexec_b64 s[6:7], vcc
	s_cbranch_execz .LBB0_971
	v_mov_b32_e32 v4, v53
	v_mad_u32_u24 v2, v2, s27, v18
	v_mul_f32_e32 v3, v3, v4
	ds_write_b32 v2, v3 offset:2048

; #define LAS __attribute__((address_space(3)))
; __device__ __forceinline__ unsigned f2bf(float f) { unsigned u = __builtin_bit_cast(unsigned, f); return (u + 0x7fffu + ((u >> 16) & 1u)) >> 16; }
; __device__ __forceinline__ int gcrow(int r, int hi) { return (r & 3) + 8 * (r >> 2) + 4 * hi; }
; __device__ __forceinline__ void gdn_chunk_prep(Frame& F) {
;     ...
;             const int j = 32 * J + r32; const float Gj = Gs[j];
; #pragma unroll
;             for (int q = 0; q < 16; ++q) {
;                 const int i = 32 * I + gcrow(q, hi);
;                 const float val = acc[q] * __expf(Gs[i] - Gj);
;                 if (typ == 0) { if (i > j) Amat[i * 68 + j] = Bs[i] * val; }
;                 else { *(LAS bf16*)((LAS unsigned char*)Tb + i * RS_K + j * 2) = (bf16)f2bf(i >= j ? val : 0.f); }
;             }
.LBB0_972:
	v_mov_b32_e32 v2, v38
	s_and_b64 vcc, exec, s[28:29]
	s_mov_b64 s[6:7], -1
	v_sub_f32_e32 v2, v2, v22
	v_mul_f32_e32 v2, 0x3fb8aa3b, v2
	v_exp_f32_e32 v3, v2
	v_or_b32_e32 v2, 8, v21
	v_mul_f32_e32 v3, v6, v3
	s_cbranch_vccnz .LBB0_974
	v_cmp_ge_u32_e32 vcc, v2, v19
	s_mov_b64 s[6:7], 0
	s_nop 0
	v_cndmask_b32_e32 v4, 0, v3, vcc
	v_bfe_u32 v5, v4, 16, 1
	v_add3_u32 v4, v4, v5, s84
	v_mad_u32_u24 v5, v2, s96, v20
	ds_write_b16_d16_hi v5, v4 offset:19456
.LBB0_974:
	s_andn2_b64 vcc, exec, s[6:7]
	s_cbranch_vccnz .LBB0_978
	v_cmp_gt_u32_e32 vcc, v2, v19
	s_and_saveexec_b64 s[6:7], vcc
	s_cbranch_execz .LBB0_977
	v_mov_b32_e32 v4, v54
	v_mad_u32_u24 v2, v2, s27, v18
	v_mul_f32_e32 v3, v3, v4
	ds_write_b32 v2, v3 offset:2048

; #define LAS __attribute__((address_space(3)))
; __device__ __forceinline__ unsigned f2bf(float f) { unsigned u = __builtin_bit_cast(unsigned, f); return (u + 0x7fffu + ((u >> 16) & 1u)) >> 16; }
; __device__ __forceinline__ int gcrow(int r, int hi) { return (r & 3) + 8 * (r >> 2) + 4 * hi; }
; __device__ __forceinline__ void gdn_chunk_prep(Frame& F) {
;     ...
;             const int j = 32 * J + r32; const float Gj = Gs[j];
; #pragma unroll
;             for (int q = 0; q < 16; ++q) {
;                 const int i = 32 * I + gcrow(q, hi);
;                 const float val = acc[q] * __expf(Gs[i] - Gj);
;                 if (typ == 0) { if (i > j) Amat[i * 68 + j] = Bs[i] * val; }
;                 else { *(LAS bf16*)((LAS unsigned char*)Tb + i * RS_K + j * 2) = (bf16)f2bf(i >= j ? val : 0.f); }
;             }
.LBB0_978:
	v_mov_b32_e32 v2, v39
	s_and_b64 vcc, exec, s[28:29]
	s_mov_b64 s[6:7], -1
	v_sub_f32_e32 v2, v2, v22
	v_mul_f32_e32 v2, 0x3fb8aa3b, v2
	v_exp_f32_e32 v3, v2
	v_or_b32_e32 v2, 9, v21
	v_mul_f32_e32 v3, v7, v3
	s_cbranch_vccnz .LBB0_980
	v_cmp_ge_u32_e32 vcc, v2, v19
	s_mov_b64 s[6:7], 0
	s_nop 0
	v_cndmask_b32_e32 v4, 0, v3, vcc
	v_bfe_u32 v5, v4, 16, 1
	v_add3_u32 v4, v4, v5, s84
	v_mad_u32_u24 v5, v2, s96, v20
	ds_write_b16_d16_hi v5, v4 offset:19456
.LBB0_980:
	s_andn2_b64 vcc, exec, s[6:7]
	s_cbranch_vccnz .LBB0_984
	v_cmp_gt_u32_e32 vcc, v2, v19
	s_and_saveexec_b64 s[6:7], vcc
	s_cbranch_execz .LBB0_983
	v_mov_b32_e32 v4, v55
	v_mad_u32_u24 v2, v2, s27, v18
	v_mul_f32_e32 v3, v3, v4
	ds_write_b32 v2, v3 offset:2048

; #define LAS __attribute__((address_space(3)))
; __device__ __forceinline__ unsigned f2bf(float f) { unsigned u = __builtin_bit_cast(unsigned, f); return (u + 0x7fffu + ((u >> 16) & 1u)) >> 16; }
; __device__ __forceinline__ int gcrow(int r, int hi) { return (r & 3) + 8 * (r >> 2) + 4 * hi; }
; __device__ __forceinline__ void gdn_chunk_prep(Frame& F) {
;     ...
;             const int j = 32 * J + r32; const float Gj = Gs[j];
; #pragma unroll
;             for (int q = 0; q < 16; ++q) {
;                 const int i = 32 * I + gcrow(q, hi);
;                 const float val = acc[q] * __expf(Gs[i] - Gj);
;                 if (typ == 0) { if (i > j) Amat[i * 68 + j] = Bs[i] * val; }
;                 else { *(LAS bf16*)((LAS unsigned char*)Tb + i * RS_K + j * 2) = (bf16)f2bf(i >= j ? val : 0.f); }
;             }
.LBB0_984:
	v_mov_b32_e32 v2, v40
	s_and_b64 vcc, exec, s[28:29]
	s_mov_b64 s[6:7], -1
	v_sub_f32_e32 v2, v2, v22
	v_mul_f32_e32 v2, 0x3fb8aa3b, v2
	v_exp_f32_e32 v3, v2
	v_or_b32_e32 v2, 10, v21
	v_mul_f32_e32 v3, v8, v3
	s_cbranch_vccnz .LBB0_986
	v_cmp_ge_u32_e32 vcc, v2, v19
	s_mov_b64 s[6:7], 0
	s_nop 0
	v_cndmask_b32_e32 v4, 0, v3, vcc
	v_bfe_u32 v5, v4, 16, 1
	v_add3_u32 v4, v4, v5, s84
	v_mad_u32_u24 v5, v2, s96, v20
	ds_write_b16_d16_hi v5, v4 offset:19456
.LBB0_986:
	s_andn2_b64 vcc, exec, s[6:7]
	s_cbranch_vccnz .LBB0_990
	v_cmp_gt_u32_e32 vcc, v2, v19
	s_and_saveexec_b64 s[6:7], vcc
	s_cbranch_execz .LBB0_989
	v_mov_b32_e32 v4, v56
	v_mad_u32_u24 v2, v2, s27, v18
	v_mul_f32_e32 v3, v3, v4
	ds_write_b32 v2, v3 offset:2048

; #define LAS __attribute__((address_space(3)))
; __device__ __forceinline__ unsigned f2bf(float f) { unsigned u = __builtin_bit_cast(unsigned, f); return (u + 0x7fffu + ((u >> 16) & 1u)) >> 16; }
; __device__ __forceinline__ int gcrow(int r, int hi) { return (r & 3) + 8 * (r >> 2) + 4 * hi; }
; __device__ __forceinline__ void gdn_chunk_prep(Frame& F) {
;     ...
;             const int j = 32 * J + r32; const float Gj = Gs[j];
; #pragma unroll
;             for (int q = 0; q < 16; ++q) {
;                 const int i = 32 * I + gcrow(q, hi);
;                 const float val = acc[q] * __expf(Gs[i] - Gj);
;                 if (typ == 0) { if (i > j) Amat[i * 68 + j] = Bs[i] * val; }
;                 else { *(LAS bf16*)((LAS unsigned char*)Tb + i * RS_K + j * 2) = (bf16)f2bf(i >= j ? val : 0.f); }
;             }
.LBB0_990:
	v_mov_b32_e32 v2, v41
	s_and_b64 vcc, exec, s[28:29]
	s_mov_b64 s[6:7], -1
	v_sub_f32_e32 v2, v2, v22
	v_mul_f32_e32 v2, 0x3fb8aa3b, v2
	v_exp_f32_e32 v3, v2
	v_or_b32_e32 v2, 11, v21
	v_mul_f32_e32 v3, v9, v3
	s_cbranch_vccnz .LBB0_992
	v_cmp_ge_u32_e32 vcc, v2, v19
	s_mov_b64 s[6:7], 0
	s_nop 0
	v_cndmask_b32_e32 v4, 0, v3, vcc
	v_bfe_u32 v5, v4, 16, 1
	v_add3_u32 v4, v4, v5, s84
	v_mad_u32_u24 v5, v2, s96, v20
	ds_write_b16_d16_hi v5, v4 offset:19456
.LBB0_992:
	s_andn2_b64 vcc, exec, s[6:7]
	s_cbranch_vccnz .LBB0_996
	v_cmp_gt_u32_e32 vcc, v2, v19
	s_and_saveexec_b64 s[6:7], vcc
	s_cbranch_execz .LBB0_995
	v_mov_b32_e32 v4, v57
	v_mad_u32_u24 v2, v2, s27, v18
	v_mul_f32_e32 v3, v3, v4
	ds_write_b32 v2, v3 offset:2048

; #define LAS __attribute__((address_space(3)))
; __device__ __forceinline__ unsigned f2bf(float f) { unsigned u = __builtin_bit_cast(unsigned, f); return (u + 0x7fffu + ((u >> 16) & 1u)) >> 16; }
; __device__ __forceinline__ int gcrow(int r, int hi) { return (r & 3) + 8 * (r >> 2) + 4 * hi; }
; __device__ __forceinline__ void gdn_chunk_prep(Frame& F) {
;     ...
;             const int j = 32 * J + r32; const float Gj = Gs[j];
; #pragma unroll
;             for (int q = 0; q < 16; ++q) {
;                 const int i = 32 * I + gcrow(q, hi);
;                 const float val = acc[q] * __expf(Gs[i] - Gj);
;                 if (typ == 0) { if (i > j) Amat[i * 68 + j] = Bs[i] * val; }
;                 else { *(LAS bf16*)((LAS unsigned char*)Tb + i * RS_K + j * 2) = (bf16)f2bf(i >= j ? val : 0.f); }
;             }
.LBB0_996:
	v_mov_b32_e32 v2, v42
	s_and_b64 vcc, exec, s[28:29]
	s_mov_b64 s[6:7], -1
	v_sub_f32_e32 v2, v2, v22
	v_mul_f32_e32 v2, 0x3fb8aa3b, v2
	v_exp_f32_e32 v3, v2
	v_or_b32_e32 v2, 16, v21
	v_mul_f32_e32 v3, v10, v3
	s_cbranch_vccnz .LBB0_998
	v_cmp_ge_u32_e32 vcc, v2, v19
	s_mov_b64 s[6:7], 0
	s_nop 0
	v_cndmask_b32_e32 v4, 0, v3, vcc
	v_bfe_u32 v5, v4, 16, 1
	v_add3_u32 v4, v4, v5, s84
	v_mad_u32_u24 v5, v2, s96, v20
	ds_write_b16_d16_hi v5, v4 offset:19456
.LBB0_998:
	s_andn2_b64 vcc, exec, s[6:7]
	s_cbranch_vccnz .LBB0_1002
	v_cmp_gt_u32_e32 vcc, v2, v19
	s_and_saveexec_b64 s[6:7], vcc
	s_cbranch_execz .LBB0_1001
	v_mov_b32_e32 v4, v58
	v_mad_u32_u24 v2, v2, s27, v18
	v_mul_f32_e32 v3, v3, v4
	ds_write_b32 v2, v3 offset:2048

; #define LAS __attribute__((address_space(3)))
; __device__ __forceinline__ unsigned f2bf(float f) { unsigned u = __builtin_bit_cast(unsigned, f); return (u + 0x7fffu + ((u >> 16) & 1u)) >> 16; }
; __device__ __forceinline__ int gcrow(int r, int hi) { return (r & 3) + 8 * (r >> 2) + 4 * hi; }
; __device__ __forceinline__ void gdn_chunk_prep(Frame& F) {
;     ...
;             const int j = 32 * J + r32; const float Gj = Gs[j];
; #pragma unroll
;             for (int q = 0; q < 16; ++q) {
;                 const int i = 32 * I + gcrow(q, hi);
;                 const float val = acc[q] * __expf(Gs[i] - Gj);
;                 if (typ == 0) { if (i > j) Amat[i * 68 + j] = Bs[i] * val; }
;                 else { *(LAS bf16*)((LAS unsigned char*)Tb + i * RS_K + j * 2) = (bf16)f2bf(i >= j ? val : 0.f); }
;             }
.LBB0_1002:
	v_mov_b32_e32 v2, v43
	s_and_b64 vcc, exec, s[28:29]
	s_mov_b64 s[6:7], -1
	v_sub_f32_e32 v2, v2, v22
	v_mul_f32_e32 v2, 0x3fb8aa3b, v2
	v_exp_f32_e32 v3, v2
	v_or_b32_e32 v2, 17, v21
	v_mul_f32_e32 v3, v11, v3
	s_cbranch_vccnz .LBB0_1004
	v_cmp_ge_u32_e32 vcc, v2, v19
	s_mov_b64 s[6:7], 0
	s_nop 0
	v_cndmask_b32_e32 v4, 0, v3, vcc
	v_bfe_u32 v5, v4, 16, 1
	v_add3_u32 v4, v4, v5, s84
	v_mad_u32_u24 v5, v2, s96, v20
	ds_write_b16_d16_hi v5, v4 offset:19456
.LBB0_1004:
	s_andn2_b64 vcc, exec, s[6:7]
	s_cbranch_vccnz .LBB0_1008
	v_cmp_gt_u32_e32 vcc, v2, v19
	s_and_saveexec_b64 s[6:7], vcc
	s_cbranch_execz .LBB0_1007
	v_mov_b32_e32 v4, v59
	v_mad_u32_u24 v2, v2, s27, v18
	v_mul_f32_e32 v3, v3, v4
	ds_write_b32 v2, v3 offset:2048

; #define LAS __attribute__((address_space(3)))
; __device__ __forceinline__ unsigned f2bf(float f) { unsigned u = __builtin_bit_cast(unsigned, f); return (u + 0x7fffu + ((u >> 16) & 1u)) >> 16; }
; __device__ __forceinline__ int gcrow(int r, int hi) { return (r & 3) + 8 * (r >> 2) + 4 * hi; }
; __device__ __forceinline__ void gdn_chunk_prep(Frame& F) {
;     ...
;             const int j = 32 * J + r32; const float Gj = Gs[j];
; #pragma unroll
;             for (int q = 0; q < 16; ++q) {
;                 const int i = 32 * I + gcrow(q, hi);
;                 const float val = acc[q] * __expf(Gs[i] - Gj);
;                 if (typ == 0) { if (i > j) Amat[i * 68 + j] = Bs[i] * val; }
;                 else { *(LAS bf16*)((LAS unsigned char*)Tb + i * RS_K + j * 2) = (bf16)f2bf(i >= j ? val : 0.f); }
;             }
.LBB0_1008:
	v_mov_b32_e32 v2, v44
	s_and_b64 vcc, exec, s[28:29]
	s_mov_b64 s[6:7], -1
	v_sub_f32_e32 v2, v2, v22
	v_mul_f32_e32 v2, 0x3fb8aa3b, v2
	v_exp_f32_e32 v3, v2
	v_or_b32_e32 v2, 18, v21
	v_mul_f32_e32 v3, v12, v3
	s_cbranch_vccnz .LBB0_1010
	v_cmp_ge_u32_e32 vcc, v2, v19
	s_mov_b64 s[6:7], 0
	s_nop 0
	v_cndmask_b32_e32 v4, 0, v3, vcc
	v_bfe_u32 v5, v4, 16, 1
	v_add3_u32 v4, v4, v5, s84
	v_mad_u32_u24 v5, v2, s96, v20
	ds_write_b16_d16_hi v5, v4 offset:19456
.LBB0_1010:
	s_andn2_b64 vcc, exec, s[6:7]
	s_cbranch_vccnz .LBB0_1014
	v_cmp_gt_u32_e32 vcc, v2, v19
	s_and_saveexec_b64 s[6:7], vcc
	s_cbranch_execz .LBB0_1013
	v_mov_b32_e32 v4, v60
	v_mad_u32_u24 v2, v2, s27, v18
	v_mul_f32_e32 v3, v3, v4
	ds_write_b32 v2, v3 offset:2048

; #define LAS __attribute__((address_space(3)))
; __device__ __forceinline__ unsigned f2bf(float f) { unsigned u = __builtin_bit_cast(unsigned, f); return (u + 0x7fffu + ((u >> 16) & 1u)) >> 16; }
; __device__ __forceinline__ int gcrow(int r, int hi) { return (r & 3) + 8 * (r >> 2) + 4 * hi; }
; __device__ __forceinline__ void gdn_chunk_prep(Frame& F) {
;     ...
;             const int j = 32 * J + r32; const float Gj = Gs[j];
; #pragma unroll
;             for (int q = 0; q < 16; ++q) {
;                 const int i = 32 * I + gcrow(q, hi);
;                 const float val = acc[q] * __expf(Gs[i] - Gj);
;                 if (typ == 0) { if (i > j) Amat[i * 68 + j] = Bs[i] * val; }
;                 else { *(LAS bf16*)((LAS unsigned char*)Tb + i * RS_K + j * 2) = (bf16)f2bf(i >= j ? val : 0.f); }
;             }
.LBB0_1014:
	v_mov_b32_e32 v2, v45
	s_and_b64 vcc, exec, s[28:29]
	s_mov_b64 s[6:7], -1
	v_sub_f32_e32 v2, v2, v22
	v_mul_f32_e32 v2, 0x3fb8aa3b, v2
	v_exp_f32_e32 v3, v2
	v_or_b32_e32 v2, 19, v21
	v_mul_f32_e32 v3, v13, v3
	s_cbranch_vccnz .LBB0_1016
	v_cmp_ge_u32_e32 vcc, v2, v19
	s_mov_b64 s[6:7], 0
	s_nop 0
	v_cndmask_b32_e32 v4, 0, v3, vcc
	v_bfe_u32 v5, v4, 16, 1
	v_add3_u32 v4, v4, v5, s84
	v_mad_u32_u24 v5, v2, s96, v20
	ds_write_b16_d16_hi v5, v4 offset:19456
.LBB0_1016:
	s_andn2_b64 vcc, exec, s[6:7]
	s_cbranch_vccnz .LBB0_1020
	v_cmp_gt_u32_e32 vcc, v2, v19
	s_and_saveexec_b64 s[6:7], vcc
	s_cbranch_execz .LBB0_1019
	v_mov_b32_e32 v4, v61
	v_mad_u32_u24 v2, v2, s27, v18
	v_mul_f32_e32 v3, v3, v4
	ds_write_b32 v2, v3 offset:2048

; #define LAS __attribute__((address_space(3)))
; __device__ __forceinline__ unsigned f2bf(float f) { unsigned u = __builtin_bit_cast(unsigned, f); return (u + 0x7fffu + ((u >> 16) & 1u)) >> 16; }
; __device__ __forceinline__ int gcrow(int r, int hi) { return (r & 3) + 8 * (r >> 2) + 4 * hi; }
; __device__ __forceinline__ void gdn_chunk_prep(Frame& F) {
;     ...
;             const int j = 32 * J + r32; const float Gj = Gs[j];
; #pragma unroll
;             for (int q = 0; q < 16; ++q) {
;                 const int i = 32 * I + gcrow(q, hi);
;                 const float val = acc[q] * __expf(Gs[i] - Gj);
;                 if (typ == 0) { if (i > j) Amat[i * 68 + j] = Bs[i] * val; }
;                 else { *(LAS bf16*)((LAS unsigned char*)Tb + i * RS_K + j * 2) = (bf16)f2bf(i >= j ? val : 0.f); }
;             }
.LBB0_1020:
	v_mov_b32_e32 v2, v46
	s_and_b64 vcc, exec, s[28:29]
	s_mov_b64 s[6:7], -1
	v_sub_f32_e32 v2, v2, v22
	v_mul_f32_e32 v2, 0x3fb8aa3b, v2
	v_exp_f32_e32 v3, v2
	v_or_b32_e32 v2, 24, v21
	v_mul_f32_e32 v3, v14, v3
	s_cbranch_vccnz .LBB0_1022
	v_cmp_ge_u32_e32 vcc, v2, v19
	s_mov_b64 s[6:7], 0
	s_nop 0
	v_cndmask_b32_e32 v4, 0, v3, vcc
	v_bfe_u32 v5, v4, 16, 1
	v_add3_u32 v4, v4, v5, s84
	v_mad_u32_u24 v5, v2, s96, v20
	ds_write_b16_d16_hi v5, v4 offset:19456
.LBB0_1022:
	s_andn2_b64 vcc, exec, s[6:7]
	s_cbranch_vccnz .LBB0_1026
	v_cmp_gt_u32_e32 vcc, v2, v19
	s_and_saveexec_b64 s[6:7], vcc
	s_cbranch_execz .LBB0_1025
	v_mov_b32_e32 v4, v62
	v_mad_u32_u24 v2, v2, s27, v18
	v_mul_f32_e32 v3, v3, v4
	ds_write_b32 v2, v3 offset:2048

; #define LAS __attribute__((address_space(3)))
; __device__ __forceinline__ unsigned f2bf(float f) { unsigned u = __builtin_bit_cast(unsigned, f); return (u + 0x7fffu + ((u >> 16) & 1u)) >> 16; }
; __device__ __forceinline__ int gcrow(int r, int hi) { return (r & 3) + 8 * (r >> 2) + 4 * hi; }
; __device__ __forceinline__ void gdn_chunk_prep(Frame& F) {
;     ...
;             const int j = 32 * J + r32; const float Gj = Gs[j];
; #pragma unroll
;             for (int q = 0; q < 16; ++q) {
;                 const int i = 32 * I + gcrow(q, hi);
;                 const float val = acc[q] * __expf(Gs[i] - Gj);
;                 if (typ == 0) { if (i > j) Amat[i * 68 + j] = Bs[i] * val; }
;                 else { *(LAS bf16*)((LAS unsigned char*)Tb + i * RS_K + j * 2) = (bf16)f2bf(i >= j ? val : 0.f); }
;             }
.LBB0_1026:
	v_mov_b32_e32 v2, v47
	s_and_b64 vcc, exec, s[28:29]
	s_mov_b64 s[6:7], -1
	v_sub_f32_e32 v2, v2, v22
	v_mul_f32_e32 v2, 0x3fb8aa3b, v2
	v_exp_f32_e32 v3, v2
	v_or_b32_e32 v2, 25, v21
	v_mul_f32_e32 v3, v15, v3
	s_cbranch_vccnz .LBB0_1028
	v_cmp_ge_u32_e32 vcc, v2, v19
	s_mov_b64 s[6:7], 0
	s_nop 0
	v_cndmask_b32_e32 v4, 0, v3, vcc
	v_bfe_u32 v5, v4, 16, 1
	v_add3_u32 v4, v4, v5, s84
	v_mad_u32_u24 v5, v2, s96, v20
	ds_write_b16_d16_hi v5, v4 offset:19456
.LBB0_1028:
	s_andn2_b64 vcc, exec, s[6:7]
	s_cbranch_vccnz .LBB0_1032
	v_cmp_gt_u32_e32 vcc, v2, v19
	s_and_saveexec_b64 s[6:7], vcc
	s_cbranch_execz .LBB0_1031
	v_mov_b32_e32 v4, v63
	v_mad_u32_u24 v2, v2, s27, v18
	v_mul_f32_e32 v3, v3, v4
	ds_write_b32 v2, v3 offset:2048

; #define LAS __attribute__((address_space(3)))
; __device__ __forceinline__ unsigned f2bf(float f) { unsigned u = __builtin_bit_cast(unsigned, f); return (u + 0x7fffu + ((u >> 16) & 1u)) >> 16; }
; __device__ __forceinline__ int gcrow(int r, int hi) { return (r & 3) + 8 * (r >> 2) + 4 * hi; }
; __device__ __forceinline__ void gdn_chunk_prep(Frame& F) {
;     ...
;             const int j = 32 * J + r32; const float Gj = Gs[j];
; #pragma unroll
;             for (int q = 0; q < 16; ++q) {
;                 const int i = 32 * I + gcrow(q, hi);
;                 const float val = acc[q] * __expf(Gs[i] - Gj);
;                 if (typ == 0) { if (i > j) Amat[i * 68 + j] = Bs[i] * val; }
;                 else { *(LAS bf16*)((LAS unsigned char*)Tb + i * RS_K + j * 2) = (bf16)f2bf(i >= j ? val : 0.f); }
;             }
.LBB0_1032:
	v_mov_b32_e32 v2, v48
	s_and_b64 vcc, exec, s[28:29]
	s_mov_b64 s[6:7], -1
	v_sub_f32_e32 v2, v2, v22
	v_mul_f32_e32 v2, 0x3fb8aa3b, v2
	v_exp_f32_e32 v3, v2
	v_or_b32_e32 v2, 26, v21
	v_mul_f32_e32 v3, v16, v3
	s_cbranch_vccnz .LBB0_1034
	v_cmp_ge_u32_e32 vcc, v2, v19
	s_mov_b64 s[6:7], 0
	s_nop 0
	v_cndmask_b32_e32 v4, 0, v3, vcc
	v_bfe_u32 v5, v4, 16, 1
	v_add3_u32 v4, v4, v5, s84
	v_mad_u32_u24 v5, v2, s96, v20
	ds_write_b16_d16_hi v5, v4 offset:19456
.LBB0_1034:
	s_andn2_b64 vcc, exec, s[6:7]
	s_cbranch_vccnz .LBB0_1038
	v_cmp_gt_u32_e32 vcc, v2, v19
	s_and_saveexec_b64 s[6:7], vcc
	s_cbranch_execz .LBB0_1037
	v_mov_b32_e32 v4, v64
	v_mad_u32_u24 v2, v2, s27, v18
	v_mul_f32_e32 v3, v3, v4
	ds_write_b32 v2, v3 offset:2048

; #define LAS __attribute__((address_space(3)))
; __device__ __forceinline__ unsigned f2bf(float f) { unsigned u = __builtin_bit_cast(unsigned, f); return (u + 0x7fffu + ((u >> 16) & 1u)) >> 16; }
; __device__ __forceinline__ int gcrow(int r, int hi) { return (r & 3) + 8 * (r >> 2) + 4 * hi; }
; __device__ __forceinline__ void gdn_chunk_prep(Frame& F) {
;     ...
;             const int j = 32 * J + r32; const float Gj = Gs[j];
; #pragma unroll
;             for (int q = 0; q < 16; ++q) {
;                 const int i = 32 * I + gcrow(q, hi);
;                 const float val = acc[q] * __expf(Gs[i] - Gj);
;                 if (typ == 0) { if (i > j) Amat[i * 68 + j] = Bs[i] * val; }
;                 else { *(LAS bf16*)((LAS unsigned char*)Tb + i * RS_K + j * 2) = (bf16)f2bf(i >= j ? val : 0.f); }
;             }
.LBB0_1038:
	v_mov_b32_e32 v2, v49
	s_and_b64 vcc, exec, s[28:29]
	s_mov_b64 s[6:7], -1
	v_sub_f32_e32 v2, v2, v22
	v_mul_f32_e32 v2, 0x3fb8aa3b, v2
	v_exp_f32_e32 v3, v2
	v_or_b32_e32 v2, 27, v21
	v_mul_f32_e32 v3, v17, v3
	s_cbranch_vccnz .LBB0_1040
	v_cmp_ge_u32_e32 vcc, v2, v19
	s_mov_b64 s[6:7], 0
	s_nop 0
	v_cndmask_b32_e32 v4, 0, v3, vcc
	v_bfe_u32 v5, v4, 16, 1
	v_add3_u32 v4, v4, v5, s84
	v_mad_u32_u24 v5, v2, s96, v20
	ds_write_b16_d16_hi v5, v4 offset:19456
.LBB0_1040:
	s_andn2_b64 vcc, exec, s[6:7]
	s_cbranch_vccnz .LBB0_1044
	v_cmp_gt_u32_e32 vcc, v2, v19
	s_and_saveexec_b64 s[6:7], vcc
	s_cbranch_execz .LBB0_1043
	v_mov_b32_e32 v4, v65
	v_mad_u32_u24 v2, v2, s27, v18
	v_mul_f32_e32 v3, v3, v4
	ds_write_b32 v2, v3 offset:2048
